# attention: static s_setprio 1 for waves 0-3 (older half) instead of waves 4-7
# speedup vs baseline: 1.0039x; 1.0009x over previous
.LBB0_955:
	s_waitcnt lgkmcnt(0)
	s_barrier
	v_readlane_b32 s100, v255, 8
	s_cmp_lt_u32 s100, 4
	s_cbranch_scc0 .Lpf_nostag
	s_setprio 1
